# grid barrier: non-leader workgroups issue the L1 invalidate at arrival (overlapping the wait) instead of after the release
# speedup vs baseline: 1.0111x; 1.0111x over previous
.LBB0_97:
	s_or_b64 exec, exec, s[8:9]
	v_cvt_f32_u32_e32 v5, v3
	s_waitcnt vmcnt(0)
	v_readfirstlane_b32 s2, v4
	v_sub_u32_e32 v4, 0, v3
	v_rcp_iflag_f32_e32 v5, v5
	v_add_u32_e32 v6, s2, v2
	v_mul_f32_e32 v5, 0x4f7ffffe, v5
	v_cvt_u32_f32_e32 v5, v5
	v_mul_lo_u32 v2, v4, v5
	v_mul_hi_u32 v2, v5, v2
	v_add_u32_e32 v2, v5, v2
	v_mul_hi_u32 v2, v6, v2
	v_mul_lo_u32 v4, v2, v3
	v_sub_u32_e32 v4, v6, v4
	v_add_u32_e32 v5, 1, v2
	v_cmp_ge_u32_e32 vcc, v4, v3
	s_nop 1
	v_cndmask_b32_e32 v2, v2, v5, vcc
	v_sub_u32_e32 v5, v4, v3
	v_cndmask_b32_e32 v4, v4, v5, vcc
	v_add_u32_e32 v5, 1, v2
	v_cmp_ge_u32_e32 vcc, v4, v3
	v_add_u32_e32 v4, 1, v6
	s_nop 0
	v_cndmask_b32_e32 v2, v2, v5, vcc
	v_mul_lo_u32 v5, v3, v2
	v_add_u32_e32 v3, v5, v3
	v_cmp_ne_u32_e32 vcc, v4, v3
	s_and_saveexec_b64 s[2:3], vcc
	s_xor_b64 s[6:7], exec, s[2:3]
	s_cbranch_execz .LBB0_111
	s_waitcnt lgkmcnt(0)
	v_mov_b32_e32 v1, 0x3500
	buffer_inv sc1
	global_load_dword v1, v1, s[64:65] sc1
	s_add_u32 s10, s64, 0x3500
	s_addc_u32 s11, s65, 0
	s_waitcnt vmcnt(0)
	v_cmp_gt_u32_e32 vcc, 1, v1
	s_and_saveexec_b64 s[8:9], vcc
	s_cbranch_execz .LBB0_110
	s_mov_b32 s2, 1
	s_mov_b64 s[12:13], 0
	v_mov_b32_e32 v1, 0
	s_branch .LBB0_101

.LBB0_110:
	s_or_b64 exec, exec, s[8:9]
	s_waitcnt vmcnt(0)
	s_waitcnt vmcnt(0)

.LBB0_197:
	s_or_b64 exec, exec, s[8:9]
	v_cvt_f32_u32_e32 v5, v3
	s_waitcnt vmcnt(0)
	v_readfirstlane_b32 s2, v4
	v_sub_u32_e32 v4, 0, v3
	v_rcp_iflag_f32_e32 v5, v5
	v_add_u32_e32 v6, s2, v2
	v_mul_f32_e32 v5, 0x4f7ffffe, v5
	v_cvt_u32_f32_e32 v5, v5
	v_mul_lo_u32 v2, v4, v5
	v_mul_hi_u32 v2, v5, v2
	v_add_u32_e32 v2, v5, v2
	v_mul_hi_u32 v2, v6, v2
	v_mul_lo_u32 v4, v2, v3
	v_sub_u32_e32 v4, v6, v4
	v_add_u32_e32 v5, 1, v2
	v_cmp_ge_u32_e32 vcc, v4, v3
	s_nop 1
	v_cndmask_b32_e32 v2, v2, v5, vcc
	v_sub_u32_e32 v5, v4, v3
	v_cndmask_b32_e32 v4, v4, v5, vcc
	v_add_u32_e32 v5, 1, v2
	v_cmp_ge_u32_e32 vcc, v4, v3
	v_add_u32_e32 v4, 1, v6
	s_nop 0
	v_cndmask_b32_e32 v2, v2, v5, vcc
	v_mul_lo_u32 v5, v3, v2
	v_add_u32_e32 v3, v5, v3
	v_cmp_ne_u32_e32 vcc, v4, v3
	s_and_saveexec_b64 s[2:3], vcc
	s_xor_b64 s[6:7], exec, s[2:3]
	s_cbranch_execz .LBB0_211
	s_waitcnt lgkmcnt(0)
	v_mov_b32_e32 v1, 0x3500
	buffer_inv sc1
	global_load_dword v1, v1, s[64:65] sc1
	s_add_u32 s10, s64, 0x3500
	s_addc_u32 s11, s65, 0
	s_waitcnt vmcnt(0)
	v_cmp_gt_u32_e32 vcc, 2, v1
	s_and_saveexec_b64 s[8:9], vcc
	s_cbranch_execz .LBB0_210
	s_mov_b32 s2, 1
	s_mov_b64 s[12:13], 0
	v_mov_b32_e32 v1, 0
	s_branch .LBB0_201

.LBB0_433:
	s_or_b64 exec, exec, s[8:9]
	v_cvt_f32_u32_e32 v5, v3
	s_waitcnt vmcnt(0)
	v_readfirstlane_b32 s2, v4
	v_sub_u32_e32 v4, 0, v3
	v_rcp_iflag_f32_e32 v5, v5
	v_add_u32_e32 v6, s2, v2
	v_mul_f32_e32 v5, 0x4f7ffffe, v5
	v_cvt_u32_f32_e32 v5, v5
	v_mul_lo_u32 v2, v4, v5
	v_mul_hi_u32 v2, v5, v2
	v_add_u32_e32 v2, v5, v2
	v_mul_hi_u32 v2, v6, v2
	v_mul_lo_u32 v4, v2, v3
	v_sub_u32_e32 v4, v6, v4
	v_add_u32_e32 v5, 1, v2
	v_cmp_ge_u32_e32 vcc, v4, v3
	s_nop 1
	v_cndmask_b32_e32 v2, v2, v5, vcc
	v_sub_u32_e32 v5, v4, v3
	v_cndmask_b32_e32 v4, v4, v5, vcc
	v_add_u32_e32 v5, 1, v2
	v_cmp_ge_u32_e32 vcc, v4, v3
	v_add_u32_e32 v4, 1, v6
	s_nop 0
	v_cndmask_b32_e32 v2, v2, v5, vcc
	v_mul_lo_u32 v5, v3, v2
	v_add_u32_e32 v3, v5, v3
	v_cmp_ne_u32_e32 vcc, v4, v3
	s_and_saveexec_b64 s[2:3], vcc
	s_xor_b64 s[6:7], exec, s[2:3]
	s_cbranch_execz .LBB0_447
	s_waitcnt lgkmcnt(0)
	v_mov_b32_e32 v1, 0x3500
	buffer_inv sc1
	global_load_dword v1, v1, s[80:81] sc1
	s_add_u32 s10, s80, 0x3500
	s_addc_u32 s11, s81, 0
	s_waitcnt vmcnt(0)
	v_cmp_gt_u32_e32 vcc, 3, v1
	s_and_saveexec_b64 s[8:9], vcc
	s_cbranch_execz .LBB0_446
	s_mov_b32 s2, 1
	s_mov_b64 s[12:13], 0
	v_mov_b32_e32 v1, 0
	s_branch .LBB0_437

.LBB0_702:
	s_or_b64 exec, exec, s[8:9]
	v_cvt_f32_u32_e32 v5, v3
	s_waitcnt vmcnt(0)
	v_readfirstlane_b32 s2, v4
	v_sub_u32_e32 v4, 0, v3
	v_rcp_iflag_f32_e32 v5, v5
	v_add_u32_e32 v6, s2, v2
	v_mul_f32_e32 v5, 0x4f7ffffe, v5
	v_cvt_u32_f32_e32 v5, v5
	v_mul_lo_u32 v2, v4, v5
	v_mul_hi_u32 v2, v5, v2
	v_add_u32_e32 v2, v5, v2
	v_mul_hi_u32 v2, v6, v2
	v_mul_lo_u32 v4, v2, v3
	v_sub_u32_e32 v4, v6, v4
	v_add_u32_e32 v5, 1, v2
	v_cmp_ge_u32_e32 vcc, v4, v3
	s_nop 1
	v_cndmask_b32_e32 v2, v2, v5, vcc
	v_sub_u32_e32 v5, v4, v3
	v_cndmask_b32_e32 v4, v4, v5, vcc
	v_add_u32_e32 v5, 1, v2
	v_cmp_ge_u32_e32 vcc, v4, v3
	v_add_u32_e32 v4, 1, v6
	s_nop 0
	v_cndmask_b32_e32 v2, v2, v5, vcc
	v_mul_lo_u32 v5, v3, v2
	v_add_u32_e32 v3, v5, v3
	v_cmp_ne_u32_e32 vcc, v4, v3
	s_and_saveexec_b64 s[2:3], vcc
	s_xor_b64 s[6:7], exec, s[2:3]
	s_cbranch_execz .LBB0_716
	s_waitcnt lgkmcnt(0)
	v_mov_b32_e32 v1, 0x3500
	buffer_inv sc1
	global_load_dword v1, v1, s[80:81] sc1
	s_add_u32 s10, s80, 0x3500
	s_addc_u32 s11, s81, 0
	s_waitcnt vmcnt(0)
	v_cmp_gt_u32_e32 vcc, 4, v1
	s_and_saveexec_b64 s[8:9], vcc
	s_cbranch_execz .LBB0_715
	s_mov_b32 s2, 1
	s_mov_b64 s[12:13], 0
	v_mov_b32_e32 v1, 0
	s_branch .LBB0_706

.LBB0_798:
	s_or_b64 exec, exec, s[8:9]
	v_cvt_f32_u32_e32 v5, v3
	s_waitcnt vmcnt(0)
	v_readfirstlane_b32 s2, v4
	v_sub_u32_e32 v4, 0, v3
	v_rcp_iflag_f32_e32 v5, v5
	v_add_u32_e32 v6, s2, v2
	v_mul_f32_e32 v5, 0x4f7ffffe, v5
	v_cvt_u32_f32_e32 v5, v5
	v_mul_lo_u32 v2, v4, v5
	v_mul_hi_u32 v2, v5, v2
	v_add_u32_e32 v2, v5, v2
	v_mul_hi_u32 v2, v6, v2
	v_mul_lo_u32 v4, v2, v3
	v_sub_u32_e32 v4, v6, v4
	v_add_u32_e32 v5, 1, v2
	v_cmp_ge_u32_e32 vcc, v4, v3
	s_nop 1
	v_cndmask_b32_e32 v2, v2, v5, vcc
	v_sub_u32_e32 v5, v4, v3
	v_cndmask_b32_e32 v4, v4, v5, vcc
	v_add_u32_e32 v5, 1, v2
	v_cmp_ge_u32_e32 vcc, v4, v3
	v_add_u32_e32 v4, 1, v6
	s_nop 0
	v_cndmask_b32_e32 v2, v2, v5, vcc
	v_mul_lo_u32 v5, v3, v2
	v_add_u32_e32 v3, v5, v3
	v_cmp_ne_u32_e32 vcc, v4, v3
	s_and_saveexec_b64 s[2:3], vcc
	s_xor_b64 s[6:7], exec, s[2:3]
	s_cbranch_execz .LBB0_812
	s_waitcnt lgkmcnt(0)
	v_mov_b32_e32 v1, 0x3500
	buffer_inv sc1
	global_load_dword v1, v1, s[80:81] sc1
	s_add_u32 s10, s80, 0x3500
	s_addc_u32 s11, s81, 0
	s_waitcnt vmcnt(0)
	v_cmp_gt_u32_e32 vcc, 5, v1
	s_and_saveexec_b64 s[8:9], vcc
	s_cbranch_execz .LBB0_811
	s_mov_b32 s2, 1
	s_mov_b64 s[12:13], 0
	v_mov_b32_e32 v1, 0
	s_branch .LBB0_802

.LBB0_868:
	s_or_b64 exec, exec, s[8:9]
	v_cvt_f32_u32_e32 v5, v3
	s_waitcnt vmcnt(0)
	v_readfirstlane_b32 s2, v4
	v_sub_u32_e32 v4, 0, v3
	v_rcp_iflag_f32_e32 v5, v5
	v_add_u32_e32 v6, s2, v2
	v_mul_f32_e32 v5, 0x4f7ffffe, v5
	v_cvt_u32_f32_e32 v5, v5
	v_mul_lo_u32 v2, v4, v5
	v_mul_hi_u32 v2, v5, v2
	v_add_u32_e32 v2, v5, v2
	v_mul_hi_u32 v2, v6, v2
	v_mul_lo_u32 v4, v2, v3
	v_sub_u32_e32 v4, v6, v4
	v_add_u32_e32 v5, 1, v2
	v_cmp_ge_u32_e32 vcc, v4, v3
	s_nop 1
	v_cndmask_b32_e32 v2, v2, v5, vcc
	v_sub_u32_e32 v5, v4, v3
	v_cndmask_b32_e32 v4, v4, v5, vcc
	v_add_u32_e32 v5, 1, v2
	v_cmp_ge_u32_e32 vcc, v4, v3
	v_add_u32_e32 v4, 1, v6
	s_nop 0
	v_cndmask_b32_e32 v2, v2, v5, vcc
	v_mul_lo_u32 v5, v3, v2
	v_add_u32_e32 v3, v5, v3
	v_cmp_ne_u32_e32 vcc, v4, v3
	s_and_saveexec_b64 s[2:3], vcc
	s_xor_b64 s[6:7], exec, s[2:3]
	s_cbranch_execz .LBB0_882
	s_waitcnt lgkmcnt(0)
	v_mov_b32_e32 v1, 0x3500
	buffer_inv sc1
	global_load_dword v1, v1, s[80:81] sc1
	s_add_u32 s10, s80, 0x3500
	s_addc_u32 s11, s81, 0
	s_waitcnt vmcnt(0)
	v_cmp_gt_u32_e32 vcc, 6, v1
	s_and_saveexec_b64 s[8:9], vcc
	s_cbranch_execz .LBB0_881
	s_mov_b32 s2, 1
	s_mov_b64 s[12:13], 0
	v_mov_b32_e32 v1, 0
	s_branch .LBB0_872

.LBB0_1059:
	s_or_b64 exec, exec, s[8:9]
	v_cvt_f32_u32_e32 v5, v3
	s_waitcnt vmcnt(0)
	v_readfirstlane_b32 s2, v4
	v_sub_u32_e32 v4, 0, v3
	v_rcp_iflag_f32_e32 v5, v5
	v_add_u32_e32 v6, s2, v2
	v_mul_f32_e32 v5, 0x4f7ffffe, v5
	v_cvt_u32_f32_e32 v5, v5
	v_mul_lo_u32 v2, v4, v5
	v_mul_hi_u32 v2, v5, v2
	v_add_u32_e32 v2, v5, v2
	v_mul_hi_u32 v2, v6, v2
	v_mul_lo_u32 v4, v2, v3
	v_sub_u32_e32 v4, v6, v4
	v_add_u32_e32 v5, 1, v2
	v_cmp_ge_u32_e32 vcc, v4, v3
	s_nop 1
	v_cndmask_b32_e32 v2, v2, v5, vcc
	v_sub_u32_e32 v5, v4, v3
	v_cndmask_b32_e32 v4, v4, v5, vcc
	v_add_u32_e32 v5, 1, v2
	v_cmp_ge_u32_e32 vcc, v4, v3
	v_add_u32_e32 v4, 1, v6
	s_nop 0
	v_cndmask_b32_e32 v2, v2, v5, vcc
	v_mul_lo_u32 v5, v3, v2
	v_add_u32_e32 v3, v5, v3
	v_cmp_ne_u32_e32 vcc, v4, v3
	s_and_saveexec_b64 s[2:3], vcc
	s_xor_b64 s[6:7], exec, s[2:3]
	s_cbranch_execz .LBB0_1073
	s_waitcnt lgkmcnt(0)
	v_mov_b32_e32 v1, 0x3500
	buffer_inv sc1
	global_load_dword v1, v1, s[80:81] sc1
	s_add_u32 s10, s80, 0x3500
	s_addc_u32 s11, s81, 0
	s_waitcnt vmcnt(0)
	v_cmp_gt_u32_e32 vcc, 7, v1
	s_and_saveexec_b64 s[8:9], vcc
	s_cbranch_execz .LBB0_1072
	s_mov_b32 s2, 1
	s_mov_b64 s[12:13], 0
	v_mov_b32_e32 v1, 0
	s_branch .LBB0_1063

.LBB0_1155:
	s_or_b64 exec, exec, s[8:9]
	v_cvt_f32_u32_e32 v5, v3
	s_waitcnt vmcnt(0)
	v_readfirstlane_b32 s2, v4
	v_sub_u32_e32 v4, 0, v3
	v_rcp_iflag_f32_e32 v5, v5
	v_add_u32_e32 v6, s2, v2
	v_mul_f32_e32 v5, 0x4f7ffffe, v5
	v_cvt_u32_f32_e32 v5, v5
	v_mul_lo_u32 v2, v4, v5
	v_mul_hi_u32 v2, v5, v2
	v_add_u32_e32 v2, v5, v2
	v_mul_hi_u32 v2, v6, v2
	v_mul_lo_u32 v4, v2, v3
	v_sub_u32_e32 v4, v6, v4
	v_add_u32_e32 v5, 1, v2
	v_cmp_ge_u32_e32 vcc, v4, v3
	s_nop 1
	v_cndmask_b32_e32 v2, v2, v5, vcc
	v_sub_u32_e32 v5, v4, v3
	v_cndmask_b32_e32 v4, v4, v5, vcc
	v_add_u32_e32 v5, 1, v2
	v_cmp_ge_u32_e32 vcc, v4, v3
	v_add_u32_e32 v4, 1, v6
	s_nop 0
	v_cndmask_b32_e32 v2, v2, v5, vcc
	v_mul_lo_u32 v5, v3, v2
	v_add_u32_e32 v3, v5, v3
	v_cmp_ne_u32_e32 vcc, v4, v3
	s_and_saveexec_b64 s[2:3], vcc
	s_xor_b64 s[6:7], exec, s[2:3]
	s_cbranch_execz .LBB0_1169
	s_waitcnt lgkmcnt(0)
	v_mov_b32_e32 v1, 0x3500
	buffer_inv sc1
	global_load_dword v1, v1, s[80:81] sc1
	s_add_u32 s10, s80, 0x3500
	s_addc_u32 s11, s81, 0
	s_waitcnt vmcnt(0)
	v_cmp_gt_u32_e32 vcc, 8, v1
	s_and_saveexec_b64 s[8:9], vcc
	s_cbranch_execz .LBB0_1168
	s_mov_b32 s2, 1
	s_mov_b64 s[12:13], 0
	v_mov_b32_e32 v1, 0
	s_branch .LBB0_1159

.LBB0_1225:
	s_or_b64 exec, exec, s[8:9]
	v_cvt_f32_u32_e32 v5, v3
	s_waitcnt vmcnt(0)
	v_readfirstlane_b32 s2, v4
	v_sub_u32_e32 v4, 0, v3
	v_rcp_iflag_f32_e32 v5, v5
	v_add_u32_e32 v6, s2, v2
	v_mul_f32_e32 v5, 0x4f7ffffe, v5
	v_cvt_u32_f32_e32 v5, v5
	v_mul_lo_u32 v2, v4, v5
	v_mul_hi_u32 v2, v5, v2
	v_add_u32_e32 v2, v5, v2
	v_mul_hi_u32 v2, v6, v2
	v_mul_lo_u32 v4, v2, v3
	v_sub_u32_e32 v4, v6, v4
	v_add_u32_e32 v5, 1, v2
	v_cmp_ge_u32_e32 vcc, v4, v3
	s_nop 1
	v_cndmask_b32_e32 v2, v2, v5, vcc
	v_sub_u32_e32 v5, v4, v3
	v_cndmask_b32_e32 v4, v4, v5, vcc
	v_add_u32_e32 v5, 1, v2
	v_cmp_ge_u32_e32 vcc, v4, v3
	v_add_u32_e32 v4, 1, v6
	s_nop 0
	v_cndmask_b32_e32 v2, v2, v5, vcc
	v_mul_lo_u32 v5, v3, v2
	v_add_u32_e32 v3, v5, v3
	v_cmp_ne_u32_e32 vcc, v4, v3
	s_and_saveexec_b64 s[2:3], vcc
	s_xor_b64 s[6:7], exec, s[2:3]
	s_cbranch_execz .LBB0_1239
	s_waitcnt lgkmcnt(0)
	v_mov_b32_e32 v1, 0x3500
	buffer_inv sc1
	global_load_dword v1, v1, s[80:81] sc1
	s_add_u32 s10, s80, 0x3500
	s_addc_u32 s11, s81, 0
	s_waitcnt vmcnt(0)
	v_cmp_gt_u32_e32 vcc, 9, v1
	s_and_saveexec_b64 s[8:9], vcc
	s_cbranch_execz .LBB0_1238
	s_mov_b32 s2, 1
	s_mov_b64 s[12:13], 0
	v_mov_b32_e32 v1, 0
	s_branch .LBB0_1229

.LBB0_1314:
	s_or_b64 exec, exec, s[8:9]
	v_cvt_f32_u32_e32 v5, v3
	s_waitcnt vmcnt(0)
	v_readfirstlane_b32 s2, v4
	v_sub_u32_e32 v4, 0, v3
	v_rcp_iflag_f32_e32 v5, v5
	v_add_u32_e32 v6, s2, v2
	v_mul_f32_e32 v5, 0x4f7ffffe, v5
	v_cvt_u32_f32_e32 v5, v5
	v_mul_lo_u32 v2, v4, v5
	v_mul_hi_u32 v2, v5, v2
	v_add_u32_e32 v2, v5, v2
	v_mul_hi_u32 v2, v6, v2
	v_mul_lo_u32 v4, v2, v3
	v_sub_u32_e32 v4, v6, v4
	v_add_u32_e32 v5, 1, v2
	v_cmp_ge_u32_e32 vcc, v4, v3
	s_nop 1
	v_cndmask_b32_e32 v2, v2, v5, vcc
	v_sub_u32_e32 v5, v4, v3
	v_cndmask_b32_e32 v4, v4, v5, vcc
	v_add_u32_e32 v5, 1, v2
	v_cmp_ge_u32_e32 vcc, v4, v3
	v_add_u32_e32 v4, 1, v6
	s_nop 0
	v_cndmask_b32_e32 v2, v2, v5, vcc
	v_mul_lo_u32 v5, v3, v2
	v_add_u32_e32 v3, v5, v3
	v_cmp_ne_u32_e32 vcc, v4, v3
	s_and_saveexec_b64 s[2:3], vcc
	s_xor_b64 s[6:7], exec, s[2:3]
	s_cbranch_execz .LBB0_1328
	s_waitcnt lgkmcnt(0)
	v_mov_b32_e32 v1, 0x3500
	buffer_inv sc1
	global_load_dword v1, v1, s[80:81] sc1
	s_add_u32 s10, s80, 0x3500
	s_addc_u32 s11, s81, 0
	s_waitcnt vmcnt(0)
	v_cmp_gt_u32_e32 vcc, 10, v1
	s_and_saveexec_b64 s[8:9], vcc
	s_cbranch_execz .LBB0_1327
	s_mov_b32 s2, 1
	s_mov_b64 s[12:13], 0
	v_mov_b32_e32 v1, 0
	s_branch .LBB0_1318

.LBB0_1592:
	s_or_b64 exec, exec, s[8:9]
	v_cvt_f32_u32_e32 v5, v3
	s_waitcnt vmcnt(0)
	v_readfirstlane_b32 s2, v4
	v_sub_u32_e32 v4, 0, v3
	v_rcp_iflag_f32_e32 v5, v5
	v_add_u32_e32 v6, s2, v2
	v_mul_f32_e32 v5, 0x4f7ffffe, v5
	v_cvt_u32_f32_e32 v5, v5
	v_mul_lo_u32 v2, v4, v5
	v_mul_hi_u32 v2, v5, v2
	v_add_u32_e32 v2, v5, v2
	v_mul_hi_u32 v2, v6, v2
	v_mul_lo_u32 v4, v2, v3
	v_sub_u32_e32 v4, v6, v4
	v_add_u32_e32 v5, 1, v2
	v_cmp_ge_u32_e32 vcc, v4, v3
	s_nop 1
	v_cndmask_b32_e32 v2, v2, v5, vcc
	v_sub_u32_e32 v5, v4, v3
	v_cndmask_b32_e32 v4, v4, v5, vcc
	v_add_u32_e32 v5, 1, v2
	v_cmp_ge_u32_e32 vcc, v4, v3
	v_add_u32_e32 v4, 1, v6
	s_nop 0
	v_cndmask_b32_e32 v2, v2, v5, vcc
	v_mul_lo_u32 v5, v3, v2
	v_add_u32_e32 v3, v5, v3
	v_cmp_ne_u32_e32 vcc, v4, v3
	s_and_saveexec_b64 s[2:3], vcc
	s_xor_b64 s[6:7], exec, s[2:3]
	s_cbranch_execz .LBB0_1606
	s_waitcnt lgkmcnt(0)
	v_mov_b32_e32 v1, 0x3500
	buffer_inv sc1
	global_load_dword v1, v1, s[80:81] sc1
	s_add_u32 s10, s80, 0x3500
	s_addc_u32 s11, s81, 0
	s_waitcnt vmcnt(0)
	v_cmp_gt_u32_e32 vcc, 11, v1
	s_and_saveexec_b64 s[8:9], vcc
	s_cbranch_execz .LBB0_1605
	s_mov_b32 s2, 1
	s_mov_b64 s[12:13], 0
	v_mov_b32_e32 v1, 0
	s_branch .LBB0_1596

.LBB0_1672:
	s_or_b64 exec, exec, s[8:9]
	v_cvt_f32_u32_e32 v5, v3
	s_waitcnt vmcnt(0)
	v_readfirstlane_b32 s2, v4
	v_sub_u32_e32 v4, 0, v3
	v_rcp_iflag_f32_e32 v5, v5
	v_add_u32_e32 v6, s2, v2
	v_mul_f32_e32 v5, 0x4f7ffffe, v5
	v_cvt_u32_f32_e32 v5, v5
	v_mul_lo_u32 v2, v4, v5
	v_mul_hi_u32 v2, v5, v2
	v_add_u32_e32 v2, v5, v2
	v_mul_hi_u32 v2, v6, v2
	v_mul_lo_u32 v4, v2, v3
	v_sub_u32_e32 v4, v6, v4
	v_add_u32_e32 v5, 1, v2
	v_cmp_ge_u32_e32 vcc, v4, v3
	s_nop 1
	v_cndmask_b32_e32 v2, v2, v5, vcc
	v_sub_u32_e32 v5, v4, v3
	v_cndmask_b32_e32 v4, v4, v5, vcc
	v_add_u32_e32 v5, 1, v2
	v_cmp_ge_u32_e32 vcc, v4, v3
	v_add_u32_e32 v4, 1, v6
	s_nop 0
	v_cndmask_b32_e32 v2, v2, v5, vcc
	v_mul_lo_u32 v5, v3, v2
	v_add_u32_e32 v3, v5, v3
	v_cmp_ne_u32_e32 vcc, v4, v3
	s_and_saveexec_b64 s[2:3], vcc
	s_xor_b64 s[6:7], exec, s[2:3]
	s_cbranch_execz .LBB0_1686
	s_waitcnt lgkmcnt(0)
	v_mov_b32_e32 v1, 0x3500
	buffer_inv sc1
	global_load_dword v1, v1, s[80:81] sc1
	s_add_u32 s10, s80, 0x3500
	s_addc_u32 s11, s81, 0
	s_waitcnt vmcnt(0)
	v_cmp_gt_u32_e32 vcc, 12, v1
	s_and_saveexec_b64 s[8:9], vcc
	s_cbranch_execz .LBB0_1685
	s_mov_b32 s2, 1
	s_mov_b64 s[12:13], 0
	v_mov_b32_e32 v1, 0
	s_branch .LBB0_1676

.LBB0_1742:
	s_or_b64 exec, exec, s[8:9]
	v_cvt_f32_u32_e32 v5, v3
	s_waitcnt vmcnt(0)
	v_readfirstlane_b32 s2, v4
	v_sub_u32_e32 v4, 0, v3
	v_rcp_iflag_f32_e32 v5, v5
	v_add_u32_e32 v6, s2, v2
	v_mul_f32_e32 v5, 0x4f7ffffe, v5
	v_cvt_u32_f32_e32 v5, v5
	v_mul_lo_u32 v2, v4, v5
	v_mul_hi_u32 v2, v5, v2
	v_add_u32_e32 v2, v5, v2
	v_mul_hi_u32 v2, v6, v2
	v_mul_lo_u32 v4, v2, v3
	v_sub_u32_e32 v4, v6, v4
	v_add_u32_e32 v5, 1, v2
	v_cmp_ge_u32_e32 vcc, v4, v3
	s_nop 1
	v_cndmask_b32_e32 v2, v2, v5, vcc
	v_sub_u32_e32 v5, v4, v3
	v_cndmask_b32_e32 v4, v4, v5, vcc
	v_add_u32_e32 v5, 1, v2
	v_cmp_ge_u32_e32 vcc, v4, v3
	v_add_u32_e32 v4, 1, v6
	s_nop 0
	v_cndmask_b32_e32 v2, v2, v5, vcc
	v_mul_lo_u32 v5, v3, v2
	v_add_u32_e32 v3, v5, v3
	v_cmp_ne_u32_e32 vcc, v4, v3
	s_and_saveexec_b64 s[2:3], vcc
	s_xor_b64 s[6:7], exec, s[2:3]
	s_cbranch_execz .LBB0_1756
	s_waitcnt lgkmcnt(0)
	v_mov_b32_e32 v1, 0x3500
	buffer_inv sc1
	global_load_dword v1, v1, s[80:81] sc1
	s_add_u32 s10, s80, 0x3500
	s_addc_u32 s11, s81, 0
	s_waitcnt vmcnt(0)
	v_cmp_gt_u32_e32 vcc, 13, v1
	s_and_saveexec_b64 s[8:9], vcc
	s_cbranch_execz .LBB0_1755
	s_mov_b32 s2, 1
	s_mov_b64 s[12:13], 0
	v_mov_b32_e32 v1, 0
	s_branch .LBB0_1746

.LBB0_1848:
	s_or_b64 exec, exec, s[8:9]
	v_cvt_f32_u32_e32 v5, v3
	s_waitcnt vmcnt(0)
	v_readfirstlane_b32 s2, v4
	v_sub_u32_e32 v4, 0, v3
	v_rcp_iflag_f32_e32 v5, v5
	v_add_u32_e32 v6, s2, v2
	v_mul_f32_e32 v5, 0x4f7ffffe, v5
	v_cvt_u32_f32_e32 v5, v5
	v_mul_lo_u32 v2, v4, v5
	v_mul_hi_u32 v2, v5, v2
	v_add_u32_e32 v2, v5, v2
	v_mul_hi_u32 v2, v6, v2
	v_mul_lo_u32 v4, v2, v3
	v_sub_u32_e32 v4, v6, v4
	v_add_u32_e32 v5, 1, v2
	v_cmp_ge_u32_e32 vcc, v4, v3
	s_nop 1
	v_cndmask_b32_e32 v2, v2, v5, vcc
	v_sub_u32_e32 v5, v4, v3
	v_cndmask_b32_e32 v4, v4, v5, vcc
	v_add_u32_e32 v5, 1, v2
	v_cmp_ge_u32_e32 vcc, v4, v3
	v_add_u32_e32 v4, 1, v6
	s_nop 0
	v_cndmask_b32_e32 v2, v2, v5, vcc
	v_mul_lo_u32 v5, v3, v2
	v_add_u32_e32 v3, v5, v3
	v_cmp_ne_u32_e32 vcc, v4, v3
	s_and_saveexec_b64 s[2:3], vcc
	s_xor_b64 s[6:7], exec, s[2:3]
	s_cbranch_execz .LBB0_1862
	s_waitcnt lgkmcnt(0)
	v_mov_b32_e32 v1, 0x3500
	buffer_inv sc1
	global_load_dword v1, v1, s[80:81] sc1
	s_add_u32 s10, s80, 0x3500
	s_addc_u32 s11, s81, 0
	s_waitcnt vmcnt(0)
	v_cmp_gt_u32_e32 vcc, 14, v1
	s_and_saveexec_b64 s[8:9], vcc
	s_cbranch_execz .LBB0_1861
	s_mov_b32 s2, 1
	s_mov_b64 s[12:13], 0
	v_mov_b32_e32 v1, 0
	s_branch .LBB0_1852

.LBB0_1941:
	s_or_b64 exec, exec, s[8:9]
	v_cvt_f32_u32_e32 v5, v3
	s_waitcnt vmcnt(0)
	v_readfirstlane_b32 s2, v4
	v_sub_u32_e32 v4, 0, v3
	v_rcp_iflag_f32_e32 v5, v5
	v_add_u32_e32 v6, s2, v2
	v_mul_f32_e32 v5, 0x4f7ffffe, v5
	v_cvt_u32_f32_e32 v5, v5
	v_mul_lo_u32 v2, v4, v5
	v_mul_hi_u32 v2, v5, v2
	v_add_u32_e32 v2, v5, v2
	v_mul_hi_u32 v2, v6, v2
	v_mul_lo_u32 v4, v2, v3
	v_sub_u32_e32 v4, v6, v4
	v_add_u32_e32 v5, 1, v2
	v_cmp_ge_u32_e32 vcc, v4, v3
	s_nop 1
	v_cndmask_b32_e32 v2, v2, v5, vcc
	v_sub_u32_e32 v5, v4, v3
	v_cndmask_b32_e32 v4, v4, v5, vcc
	v_add_u32_e32 v5, 1, v2
	v_cmp_ge_u32_e32 vcc, v4, v3
	v_add_u32_e32 v4, 1, v6
	s_nop 0
	v_cndmask_b32_e32 v2, v2, v5, vcc
	v_mul_lo_u32 v5, v3, v2
	v_add_u32_e32 v3, v5, v3
	v_cmp_ne_u32_e32 vcc, v4, v3
	s_and_saveexec_b64 s[2:3], vcc
	s_xor_b64 s[6:7], exec, s[2:3]
	s_cbranch_execz .LBB0_1955
	s_waitcnt lgkmcnt(0)
	v_mov_b32_e32 v1, 0x3500
	buffer_inv sc1
	global_load_dword v1, v1, s[80:81] sc1
	s_add_u32 s10, s80, 0x3500
	s_addc_u32 s11, s81, 0
	s_waitcnt vmcnt(0)
	v_cmp_gt_u32_e32 vcc, 15, v1
	s_and_saveexec_b64 s[8:9], vcc
	s_cbranch_execz .LBB0_1954
	s_mov_b32 s2, 1
	s_mov_b64 s[12:13], 0
	v_mov_b32_e32 v1, 0
	s_branch .LBB0_1945
